# mixer C LDS tile: time index XOR-swizzled by channel group (writer ds_write_b16 and reader ds_read_b128 agree) to remove the bank conflicts of the transposing stores
# speedup vs baseline: 1.0078x; 1.0078x over previous
.LBB0_1088:
	global_load_dwordx4 v[4:7], v[24:25], off
	global_load_dwordx4 v[8:11], v[24:25], off offset:16
	s_lshl_b32 s2, s8, 5
	s_add_i32 s6, s2, 0x8000
	s_lshl_b32 s2, s8, 7
	s_add_i32 s7, s2, 0xfffffc00
	s_cmp_gt_i32 s8, 7
	s_cselect_b64 s[4:5], -1, 0
	s_and_b64 s[2:3], s[4:5], exec
	s_cselect_b32 s3, -1, s8
	s_cselect_b32 s9, 8, 2
	s_cselect_b32 s2, s7, s6
	s_cmp_gt_i32 s3, -1
	s_cselect_b64 s[6:7], -1, 0
	s_add_i32 s24, s3, s53
	s_ashr_i32 s3, s2, 31
	v_lshl_add_u64 v[12:13], v[22:23], 0, s[2:3]
	s_lshl_b64 s[10:11], s[24:25], 15
	v_mad_u64_u32 v[40:41], s[16:17], v12, s69, v[26:27]
	v_mad_i32_i24 v41, v13, s69, v41
	v_lshl_add_u64 v[42:43], v[28:29], 0, s[10:11]
	v_readlane_b32 s100, v254, 9
	v_bfe_u32 v104, v52, 2, 3
	v_and_b32_e32 v105, 2, v52
	v_lshlrev_b32_e32 v105, 3, v105
	v_xor_b32_e32 v105, v105, v59
	s_mov_b32 s101, 0
	s_lshr_b32 s100, s100, 4
	v_lshl_add_u32 v2, v104, 5, v105
	s_branch .LBB0_1090
.LBB0_1089:
	s_add_i32 s9, s9, -1
	s_mov_b64 s[10:11], 0x4000
	s_add_i32 s101, s101, 1
	v_xor_b32_e32 v2, s101, v104
	v_lshl_add_u32 v2, v2, 5, v105
	v_lshl_add_u64 v[40:41], v[40:41], 0, s[48:49]
	s_cmp_eq_u32 s9, 0
	v_lshl_add_u64 v[42:43], v[42:43], 0, s[10:11]
	s_cbranch_scc1 .LBB0_1092

.LBB0_1094:
	s_add_i32 s6, s4, s19
	v_lshl_or_b32 v73, s6, 4, v21
	v_add_u32_e32 v74, s20, v73
	v_mov_b32_e32 v75, 0
	v_lshl_add_u64 v[74:75], v[74:75], 2, s[0:1]
	global_load_dword v72, v[74:75], off
	v_add_u32_e32 v73, s2, v73
	v_mov_b64_e32 v[74:75], s[14:15]
	v_mad_i64_i32 v[74:75], s[6:7], v73, s69, v[74:75]
	s_mov_b64 s[6:7], 0x7900e00
	v_mov_b32_e32 v76, v32
	v_mov_b32_e32 v77, 0
	v_lshl_add_u64 v[74:75], v[74:75], 0, s[6:7]
	s_nop 0
	v_lshl_add_u64 v[74:75], v[74:75], 0, v[76:77]
	global_load_dwordx2 v[64:65], v[74:75], off
	global_load_dwordx2 v[66:67], v[74:75], off offset:32
	global_load_dwordx2 v[68:69], v[74:75], off offset:64
	global_load_dwordx2 v[70:71], v[74:75], off offset:96
	s_lshr_b32 s6, s5, 5
	v_mov_b32_e32 v16, 0
	s_add_i32 s6, s6, 1
	v_mov_b64_e32 v[42:43], v[40:41]
	v_lshrrev_b32_e32 v94, 4, v53
	v_sub_u32_e32 v95, v58, v53
	v_mov_b32_e32 v17, v16
	v_mov_b32_e32 v18, v16
	v_mov_b32_e32 v19, v16
	v_mov_b32_e32 v12, v16
	v_mov_b32_e32 v13, v16
	v_mov_b32_e32 v14, v16
	v_mov_b32_e32 v15, v16
	v_mov_b32_e32 v8, v16
	v_mov_b32_e32 v9, v16
	v_mov_b32_e32 v10, v16
	v_mov_b32_e32 v11, v16
	v_mov_b32_e32 v4, v16
	v_mov_b32_e32 v5, v16
	v_mov_b32_e32 v6, v16
	v_mov_b32_e32 v7, v16
	global_load_dwordx4 v[44:47], v[42:43], off
	v_lshl_add_u64 v[42:43], v[42:43], 0, 64
.LBB0_1095:
	v_xor_b32_e32 v100, s100, v94
	v_xor_b32_e32 v101, 1, v100
	v_xor_b32_e32 v102, 2, v100
	v_xor_b32_e32 v103, 3, v100
	v_lshl_add_u32 v100, v100, 4, v95
	v_lshl_add_u32 v101, v101, 4, v95
	v_lshl_add_u32 v102, v102, 4, v95
	v_lshl_add_u32 v103, v103, 4, v95
	ds_read_b128 v[48:51], v100
	ds_read_b128 v[78:81], v101 offset:4352
	ds_read_b128 v[82:85], v102 offset:8704
	ds_read_b128 v[86:89], v103 offset:13056
	s_add_i32 s6, s6, -1
	v_add_u32_e32 v94, 4, v94
	s_cmp_eq_u32 s6, 0
	s_waitcnt vmcnt(0)
	v_mov_b32_e32 v90, v44
	v_mov_b32_e32 v91, v45
	v_mov_b32_e32 v92, v46
	v_mov_b32_e32 v93, v47
	s_cbranch_scc1 .Lmc_ks_last
	global_load_dwordx4 v[44:47], v[42:43], off
	v_lshl_add_u64 v[42:43], v[42:43], 0, 64
